# MLA loop: MFMA/VALU interleave - PV MFMAs of the first key half issued under the exp of the second half (3 v_exp per MFMA), row-sum reduction under the last PV MFMAs
# speedup vs baseline: 1.0084x; 1.0062x over previous
; #define MFMA(a, b, c) __builtin_amdgcn_mfma_f32_32x32x16_bf16((a), (b), (c), 0, 0, 0)
; DI unsigned pk2(float a, float b) { f2_t v = {a, b}; bf2_t r = __builtin_convertvector(v, bf2_t); return __builtin_bit_cast(unsigned, r); }
; DI float xhalf_sum(float x) { const auto rr = __builtin_amdgcn_permlane32_swap(__float_as_uint(x), __float_as_uint(x), false, false); return __uint_as_float(rr[0]) + __uint_as_float(rr[1]); }
; template <int DQK, int DV, bool BAND> ...
;     ...
;       const float m_ref = (m_run == -INFINITY) ? 0.f : m_run;
;       float rs0 = 0.f, rs1 = 0.f;
; #pragma unroll
;       for (int r = 0; r < 16; ++r) { const float e0 = __builtin_amdgcn_exp2f(p0[r] - m_ref), e1 = __builtin_amdgcn_exp2f(p1[r] - m_ref); p0[r] = e0; p1[r] = e1; rs0 += e0; rs1 += e1; }
;       l_run += xhalf_sum(rs0 + rs1);
;       __builtin_amdgcn_s_setprio(1);
; #pragma unroll
;       for (int s = 0; s < 2; ++s) {
;         const u32x4 pu0 = {pk2(p0[8 * s], p0[8 * s + 1]), pk2(p0[8 * s + 2], p0[8 * s + 3]), pk2(p0[8 * s + 4], p0[8 * s + 5]), pk2(p0[8 * s + 6], p0[8 * s + 7])};
;         const u32x4 pu1 = {pk2(p1[8 * s], p1[8 * s + 1]), pk2(p1[8 * s + 2], p1[8 * s + 3]), pk2(p1[8 * s + 4], p1[8 * s + 5]), pk2(p1[8 * s + 6], p1[8 * s + 7])};
; #pragma unroll
;         for (int cb = 0; cb < NCB; ++cb) {
;           const u32x2 lo0 = *(const u32x2*)&Vs[(cb * 32 + r32) * VLD + 16 * s + 4 * hi];
;           const u32x2 hi0 = *(const u32x2*)&Vs[(cb * 32 + r32) * VLD + 16 * s + 4 * hi + 8];
;           const u32x4 v0 = {lo0[0], lo0[1], hi0[0], hi0[1]};
;           o[cb] = MFMA(__builtin_bit_cast(bf16x8, pu0), __builtin_bit_cast(bf16x8, v0), o[cb]);
;         }
; #pragma unroll
;         for (int cb = 0; cb < NCB; ++cb) {
;           const u32x2 lo1 = *(const u32x2*)&Vs[(cb * 32 + r32) * VLD + 32 + 16 * s + 4 * hi];
;           const u32x2 hi1 = *(const u32x2*)&Vs[(cb * 32 + r32) * VLD + 32 + 16 * s + 4 * hi + 8];
;           const u32x4 v1 = {lo1[0], lo1[1], hi1[0], hi1[1]};
;           o[cb] = MFMA(__builtin_bit_cast(bf16x8, pu1), __builtin_bit_cast(bf16x8, v1), o[cb]);
;         }
;       }
;       __builtin_amdgcn_s_setprio(0);
.LBB1_325:
	v_exp_f32_e32 v34, v34
	v_exp_f32_e32 v35, v35
	v_exp_f32_e32 v36, v36
	v_exp_f32_e32 v37, v37
	v_exp_f32_e32 v38, v38
	v_exp_f32_e32 v39, v39
	v_exp_f32_e32 v40, v40
	v_exp_f32_e32 v41, v41
	v_exp_f32_e32 v42, v42
	v_exp_f32_e32 v43, v43
	v_exp_f32_e32 v44, v44
	v_exp_f32_e32 v45, v45
	v_exp_f32_e32 v46, v46
	v_exp_f32_e32 v47, v47
	v_exp_f32_e32 v48, v48
	v_exp_f32_e32 v49, v49
	s_nop 0
	v_pk_add_f32 v[168:169], v[34:35], v[36:37]
	v_pk_add_f32 v[170:171], v[38:39], v[40:41]
	v_pk_add_f32 v[168:169], v[42:43], v[168:169]
	v_pk_add_f32 v[170:171], v[44:45], v[170:171]
	v_pk_add_f32 v[168:169], v[46:47], v[168:169]
	v_pk_add_f32 v[170:171], v[48:49], v[170:171]
	v_cvt_pk_bf16_f32 v34, v34, v35
	v_cvt_pk_bf16_f32 v35, v36, v37
	v_cvt_pk_bf16_f32 v36, v38, v39
	v_cvt_pk_bf16_f32 v37, v40, v41
	v_cvt_pk_bf16_f32 v38, v42, v43
	v_cvt_pk_bf16_f32 v39, v44, v45
	v_cvt_pk_bf16_f32 v40, v46, v47
	v_cvt_pk_bf16_f32 v41, v48, v49
	v_exp_f32_e32 v50, v50
	v_exp_f32_e32 v51, v51
	v_exp_f32_e32 v52, v52
	s_waitcnt lgkmcnt(0)
	v_mfma_f32_32x32x16_bf16 v[2:17], v[34:37], v[208:211], v[2:17]
	v_exp_f32_e32 v53, v53
	v_exp_f32_e32 v54, v54
	v_exp_f32_e32 v55, v55
	v_mfma_f32_32x32x16_bf16 v[18:33], v[34:37], v[212:215], v[18:33]
	v_exp_f32_e32 v56, v56
	v_exp_f32_e32 v57, v57
	v_exp_f32_e32 v58, v58
	v_mfma_f32_32x32x16_bf16 v[2:17], v[38:41], v[224:227], v[2:17]
	v_exp_f32_e32 v59, v59
	v_exp_f32_e32 v60, v60
	v_exp_f32_e32 v61, v61
	v_mfma_f32_32x32x16_bf16 v[18:33], v[38:41], v[228:231], v[18:33]
	v_exp_f32_e32 v62, v62
	v_exp_f32_e32 v63, v63
	v_exp_f32_e32 v64, v64
	v_exp_f32_e32 v65, v65
	s_nop 0
	v_pk_add_f32 v[168:169], v[50:51], v[168:169]
	v_pk_add_f32 v[170:171], v[52:53], v[170:171]
	v_pk_add_f32 v[168:169], v[54:55], v[168:169]
	v_pk_add_f32 v[170:171], v[56:57], v[170:171]
	v_pk_add_f32 v[168:169], v[58:59], v[168:169]
	v_pk_add_f32 v[170:171], v[60:61], v[170:171]
	v_pk_add_f32 v[168:169], v[62:63], v[168:169]
	v_pk_add_f32 v[170:171], v[64:65], v[170:171]
	v_cvt_pk_bf16_f32 v50, v50, v51
	v_cvt_pk_bf16_f32 v51, v52, v53
	v_cvt_pk_bf16_f32 v52, v54, v55
	v_cvt_pk_bf16_f32 v53, v56, v57
	v_cvt_pk_bf16_f32 v54, v58, v59
	v_cvt_pk_bf16_f32 v55, v60, v61
	v_cvt_pk_bf16_f32 v56, v62, v63
	v_cvt_pk_bf16_f32 v57, v64, v65
	v_pk_add_f32 v[168:169], v[168:169], v[170:171]
	v_mfma_f32_32x32x16_bf16 v[2:17], v[50:53], v[216:219], v[2:17]
	v_add_f32_e32 v168, v168, v169
	v_mov_b32_e32 v169, v168
	v_mfma_f32_32x32x16_bf16 v[18:33], v[50:53], v[220:223], v[18:33]
	s_nop 0
	v_permlane32_swap_b32_e32 v168, v169
	v_mfma_f32_32x32x16_bf16 v[2:17], v[54:57], v[232:235], v[2:17]
	v_add_f32_e32 v168, v168, v169
	v_add_f32_e32 v126, v126, v168
	v_mfma_f32_32x32x16_bf16 v[18:33], v[54:57], v[236:239], v[18:33]
	s_add_u32 s12, s12, s8
	s_addc_u32 s13, s13, s9
	s_add_u32 s14, s14, s10
	s_addc_u32 s15, s15, s11
	s_cmp_eq_u32 s75, s21
	s_cbranch_scc1 .LBB1_327
	v_mov_b32_e32 v133, v0
	s_branch .LBB1_318
